# SSD part 2 tail: the 8 group-norm weight loads issued together before the stores (no vmcnt(0) between stores)
# speedup vs baseline: 1.0015x; 1.0015x over previous
; #define LAS __attribute__((address_space(3)))
; DI float silu_f(float x) { return x * __builtin_amdgcn_rcpf(1.f + __expf(-x)); }
; DI void ssd_part2_unit(int u, const bf16* PROJ, const float* DT, const float* cw, const float* cb, const float* a_log_l, const float* dskip_l, const float* snw_l,
;                        const float* STATES, bf16* YC, LAS unsigned char* ldsu, int tid, int wave, int lane) {
;     ...
;     const int token = t0 + lq; float ss = 0.f;
; #pragma unroll
;     for (int hh = 0; hh < 2; ++hh) { const float dsk = dskip_l[2 * grp + hh];
; #pragma unroll
;         for (int pt = 0; pt < 4; ++pt) { const int ch = hh * 64 + 16 * pt + 4 * g;
;             const u32x2 xv = *(const LAS u32x2*)(XS + lq * IMG_PITCH + ch * 2);
;             const u32x2 zv = *(const u32x2*)(slab(PROJ, C_CZ + grp * 128 + hh * 64, b) + (size_t)token * 64 + 16 * pt + 4 * g);
;             f32x4 y = acc[hh][pt];
;             y[0] = (y[0] + dsk * bflo(xv.x)) * silu_f(bflo(zv.x)); y[1] = (y[1] + dsk * bfhi(xv.x)) * silu_f(bfhi(zv.x));
;             y[2] = (y[2] + dsk * bflo(xv.y)) * silu_f(bflo(zv.y)); y[3] = (y[3] + dsk * bfhi(xv.y)) * silu_f(bfhi(zv.y));
;             acc[hh][pt] = y; ss += (y[0] * y[0] + y[1] * y[1]) + (y[2] * y[2] + y[3] * y[3]); } }
.LBB0_472:
	s_lshl_b32 s0, s57, 22
	s_lshl_b32 s1, s89, 2
	s_add_u32 s0, s10, s0
	v_add_u32_e32 v52, s75, v202
	v_mov_b32_e32 v18, s1
	s_addc_u32 s1, s11, 0
	v_ashrrev_i32_e32 v53, 31, v52
	s_add_u32 s0, s0, s62
	v_lshlrev_b64 v[16:17], 7, v[52:53]
	s_addc_u32 s1, s1, s63
	v_lshlrev_b32_e32 v188, 1, v204
	v_lshl_add_u64 v[16:17], s[0:1], 0, v[16:17]
	v_lshl_add_u64 v[56:57], v[16:17], 0, v[188:189]
	s_mov_b64 s[0:1], 0x4000000
	v_lshl_add_u64 v[16:17], v[56:57], 0, s[0:1]
	s_brev_b32 s0, 32
	global_load_dwordx2 v[54:55], v18, s[54:55]
	v_add_co_u32_e32 v18, vcc, s0, v56
	ds_read2_b64 v[24:27], v231 offset1:4
	s_nop 0
	v_addc_co_u32_e32 v19, vcc, 0, v57, vcc
	global_load_dwordx2 v[18:19], v[18:19], off
	s_mov_b64 s[0:1], 0x4200000
	s_waitcnt lgkmcnt(0)
	v_lshlrev_b32_e32 v28, 16, v24
	v_and_b32_e32 v29, 0xffff0000, v24
	v_lshlrev_b32_e32 v24, 16, v25
	v_and_b32_e32 v25, 0xffff0000, v25
	v_lshlrev_b32_e32 v30, 16, v26
	v_and_b32_e32 v31, 0xffff0000, v26
	s_add_i32 s2, s2, s88
	s_cmpk_gt_i32 s2, 0xff
	s_mov_b32 s89, 0x2aaaaaab
	s_waitcnt vmcnt(1)
	v_pk_fma_f32 v[24:25], v[54:55], v[24:25], v[50:51] op_sel_hi:[0,1,1]
	v_pk_fma_f32 v[28:29], v[54:55], v[28:29], v[48:49] op_sel_hi:[0,1,1]
	v_pk_fma_f32 v[30:31], v[54:55], v[30:31], v[44:45] op_sel_hi:[0,1,1]
	s_waitcnt vmcnt(0)
	v_lshlrev_b32_e32 v20, 16, v18
	v_and_b32_e32 v21, 0xffff0000, v18
	v_mul_f32_e32 v18, 0xbfb8aa3b, v20
	v_exp_f32_e32 v18, v18
	s_nop 0
	v_add_f32_e32 v18, 1.0, v18
	v_rcp_f32_e32 v22, v18
	v_mul_f32_e32 v18, 0xbfb8aa3b, v21
	v_exp_f32_e32 v18, v18
	s_nop 0
	v_add_f32_e32 v18, 1.0, v18
	v_rcp_f32_e32 v23, v18
	v_lshlrev_b32_e32 v18, 16, v19
	v_and_b32_e32 v19, 0xffff0000, v19
	v_pk_mul_f32 v[20:21], v[22:23], v[20:21]
	v_mul_f32_e32 v22, 0xbfb8aa3b, v18
	v_mul_f32_e32 v23, 0xbfb8aa3b, v19
	v_exp_f32_e32 v22, v22
	v_exp_f32_e32 v23, v23
	v_pk_mul_f32 v[20:21], v[28:29], v[20:21]
	v_add_f32_e32 v22, 1.0, v22
	v_add_f32_e32 v23, 1.0, v23
	v_rcp_f32_e32 v22, v22
	v_rcp_f32_e32 v23, v23
	s_nop 0
	v_pk_mul_f32 v[18:19], v[22:23], v[18:19]
	s_nop 0
	v_pk_mul_f32 v[22:23], v[24:25], v[18:19]
	global_load_dwordx2 v[18:19], v[16:17], off offset:32
	s_waitcnt vmcnt(0)
	v_lshlrev_b32_e32 v24, 16, v18
	v_and_b32_e32 v25, 0xffff0000, v18
	v_mul_f32_e32 v18, 0xbfb8aa3b, v24
	v_exp_f32_e32 v18, v18
	s_nop 0
	v_add_f32_e32 v18, 1.0, v18
	v_rcp_f32_e32 v28, v18
	v_mul_f32_e32 v18, 0xbfb8aa3b, v25
	v_exp_f32_e32 v18, v18
	s_nop 0
	v_add_f32_e32 v18, 1.0, v18
	v_rcp_f32_e32 v29, v18
	v_lshlrev_b32_e32 v18, 16, v19
	v_and_b32_e32 v19, 0xffff0000, v19
	v_mul_f32_e32 v26, 0xbfb8aa3b, v18
	v_pk_mul_f32 v[24:25], v[28:29], v[24:25]
	v_lshlrev_b32_e32 v28, 16, v27
	v_and_b32_e32 v29, 0xffff0000, v27
	v_mul_f32_e32 v27, 0xbfb8aa3b, v19
	v_exp_f32_e32 v26, v26
	v_exp_f32_e32 v27, v27
	v_pk_mul_f32 v[24:25], v[30:31], v[24:25]
	v_pk_fma_f32 v[28:29], v[54:55], v[28:29], v[46:47] op_sel_hi:[0,1,1]
	v_add_f32_e32 v26, 1.0, v26
	v_add_f32_e32 v27, 1.0, v27
	v_rcp_f32_e32 v26, v26
	v_rcp_f32_e32 v27, v27
	v_mov_b32_e32 v30, v23
	ds_read2_b64 v[46:49], v231 offset0:8 offset1:12
	v_pk_mul_f32 v[18:19], v[26:27], v[18:19]
	s_nop 0
	v_pk_mul_f32 v[26:27], v[28:29], v[18:19]
	v_mov_b32_e32 v28, v21
	v_mov_b32_e32 v29, v25
	v_mov_b32_e32 v18, v20
	v_mov_b32_e32 v19, v24
	v_pk_mul_f32 v[28:29], v[28:29], v[28:29]
	v_mov_b32_e32 v31, v27
	v_pk_fma_f32 v[18:19], v[18:19], v[18:19], v[28:29]
	v_mov_b32_e32 v28, v22
	v_mov_b32_e32 v29, v26
	v_pk_mul_f32 v[30:31], v[30:31], v[30:31]
	s_waitcnt lgkmcnt(0)
	v_lshlrev_b32_e32 v50, 16, v46
	v_pk_fma_f32 v[28:29], v[28:29], v[28:29], v[30:31]
	v_and_b32_e32 v51, 0xffff0000, v46
	v_pk_add_f32 v[18:19], v[18:19], v[28:29]
	v_pk_fma_f32 v[40:41], v[54:55], v[50:51], v[40:41] op_sel_hi:[0,1,1]
	v_pk_add_f32 v[44:45], v[18:19], v[18:19] op_sel:[0,1] op_sel_hi:[1,0]
	global_load_dwordx2 v[18:19], v[16:17], off offset:64
	v_lshlrev_b32_e32 v46, 16, v48
	global_load_dwordx2 v[16:17], v[16:17], off offset:96
	s_waitcnt vmcnt(1)
	v_lshlrev_b32_e32 v28, 16, v18
	v_and_b32_e32 v29, 0xffff0000, v18
	v_mul_f32_e32 v18, 0xbfb8aa3b, v28
	v_exp_f32_e32 v18, v18
	s_nop 0
	v_add_f32_e32 v18, 1.0, v18
	v_rcp_f32_e32 v30, v18
	v_mul_f32_e32 v18, 0xbfb8aa3b, v29
	v_exp_f32_e32 v18, v18
	s_nop 0
	v_add_f32_e32 v18, 1.0, v18
	v_rcp_f32_e32 v31, v18
	v_lshlrev_b32_e32 v18, 16, v19
	v_and_b32_e32 v19, 0xffff0000, v19
	v_pk_mul_f32 v[28:29], v[30:31], v[28:29]
	v_mul_f32_e32 v30, 0xbfb8aa3b, v18
	v_mul_f32_e32 v31, 0xbfb8aa3b, v19
	v_exp_f32_e32 v30, v30
	v_exp_f32_e32 v31, v31
	v_pk_mul_f32 v[28:29], v[40:41], v[28:29]
	v_lshlrev_b32_e32 v40, 16, v47
	v_add_f32_e32 v30, 1.0, v30
	v_add_f32_e32 v31, 1.0, v31
	v_rcp_f32_e32 v30, v30
	v_rcp_f32_e32 v31, v31
	v_and_b32_e32 v41, 0xffff0000, v47
	v_pk_fma_f32 v[40:41], v[54:55], v[40:41], v[42:43] op_sel_hi:[0,1,1]
	v_and_b32_e32 v47, 0xffff0000, v48
	v_pk_mul_f32 v[18:19], v[30:31], v[18:19]
	v_pk_fma_f32 v[36:37], v[54:55], v[46:47], v[36:37] op_sel_hi:[0,1,1]
	v_pk_mul_f32 v[30:31], v[40:41], v[18:19]
	v_mov_b32_e32 v40, v29
	v_mov_b32_e32 v41, v31
	v_mov_b32_e32 v18, v28
	v_mov_b32_e32 v19, v30
	v_pk_mul_f32 v[40:41], v[40:41], v[40:41]
	s_nop 0
	v_pk_fma_f32 v[18:19], v[18:19], v[18:19], v[40:41]
	s_nop 0
	v_pk_add_f32 v[42:43], v[18:19], v[18:19] op_sel:[0,1] op_sel_hi:[1,0]
	s_waitcnt vmcnt(0)
; #define LAS __attribute__((address_space(3)))
; DI float silu_f(float x) { return x * __builtin_amdgcn_rcpf(1.f + __expf(-x)); }
; DI void ssd_part2_unit(int u, const bf16* PROJ, const float* DT, const float* cw, const float* cb, const float* a_log_l, const float* dskip_l, const float* snw_l,
;                        const float* STATES, bf16* YC, LAS unsigned char* ldsu, int tid, int wave, int lane) {
;     ...
;     const int token = t0 + lq; float ss = 0.f;
; #pragma unroll
;     for (int hh = 0; hh < 2; ++hh) { const float dsk = dskip_l[2 * grp + hh];
; #pragma unroll
;         for (int pt = 0; pt < 4; ++pt) { const int ch = hh * 64 + 16 * pt + 4 * g;
;             const u32x2 xv = *(const LAS u32x2*)(XS + lq * IMG_PITCH + ch * 2);
;             const u32x2 zv = *(const u32x2*)(slab(PROJ, C_CZ + grp * 128 + hh * 64, b) + (size_t)token * 64 + 16 * pt + 4 * g);
;             f32x4 y = acc[hh][pt];
;             y[0] = (y[0] + dsk * bflo(xv.x)) * silu_f(bflo(zv.x)); y[1] = (y[1] + dsk * bfhi(xv.x)) * silu_f(bfhi(zv.x));
;             y[2] = (y[2] + dsk * bflo(xv.y)) * silu_f(bflo(zv.y)); y[3] = (y[3] + dsk * bfhi(xv.y)) * silu_f(bfhi(zv.y));
;             acc[hh][pt] = y; ss += (y[0] * y[0] + y[1] * y[1]) + (y[2] * y[2] + y[3] * y[3]); } }
	v_lshlrev_b32_e32 v18, 16, v16
	v_and_b32_e32 v19, 0xffff0000, v16
	v_mul_f32_e32 v16, 0xbfb8aa3b, v18
	v_exp_f32_e32 v16, v16
	s_nop 0
	v_add_f32_e32 v16, 1.0, v16
	v_rcp_f32_e32 v40, v16
	v_mul_f32_e32 v16, 0xbfb8aa3b, v19
	v_exp_f32_e32 v16, v16
	s_nop 0
	v_add_f32_e32 v16, 1.0, v16
	v_rcp_f32_e32 v41, v16
	v_lshlrev_b32_e32 v16, 16, v17
	v_and_b32_e32 v17, 0xffff0000, v17
	v_pk_mul_f32 v[18:19], v[40:41], v[18:19]
	v_lshlrev_b32_e32 v40, 16, v49
	v_and_b32_e32 v41, 0xffff0000, v49
	v_pk_fma_f32 v[38:39], v[54:55], v[40:41], v[38:39] op_sel_hi:[0,1,1]
	v_lshl_add_u64 v[40:41], v[56:57], 0, s[0:1]
	s_mov_b32 s0, 0x4200000
	v_add_co_u32_e32 v50, vcc, s0, v56
	v_pk_mul_f32 v[36:37], v[36:37], v[18:19]
	s_nop 0
	v_addc_co_u32_e32 v51, vcc, 0, v57, vcc
	global_load_dwordx2 v[50:51], v[50:51], off
	v_mul_f32_e32 v18, 0xbfb8aa3b, v16
	v_mul_f32_e32 v19, 0xbfb8aa3b, v17
	v_exp_f32_e32 v18, v18
	v_exp_f32_e32 v19, v19
	v_add_f32_e32 v18, 1.0, v18
	v_add_f32_e32 v19, 1.0, v19
	v_rcp_f32_e32 v18, v18
	v_rcp_f32_e32 v19, v19
	s_waitcnt vmcnt(0)
	v_lshlrev_b32_e32 v56, 16, v50
	v_pk_mul_f32 v[16:17], v[18:19], v[16:17]
	v_and_b32_e32 v57, 0xffff0000, v50
	v_pk_mul_f32 v[38:39], v[38:39], v[16:17]
	v_mul_f32_e32 v16, v37, v37
	v_pk_fma_f32 v[46:47], v[36:37], v[36:37], v[16:17] op_sel_hi:[1,1,0]
	v_mul_f32_e32 v16, v39, v39
	v_pk_fma_f32 v[48:49], v[38:39], v[38:39], v[16:17] op_sel_hi:[1,1,0]
	ds_read2_b64 v[16:19], v231 offset0:16 offset1:20
	v_mul_f32_e32 v43, 0xbfb8aa3b, v56
	v_exp_f32_e32 v43, v43
	v_lshlrev_b32_e32 v50, 16, v51
	v_and_b32_e32 v51, 0xffff0000, v51
	s_waitcnt lgkmcnt(0)
	v_lshlrev_b32_e32 v60, 16, v16
	v_and_b32_e32 v61, 0xffff0000, v16
	v_mul_f32_e32 v16, 0xbfb8aa3b, v57
	v_exp_f32_e32 v16, v16
	v_add_f32_e32 v43, 1.0, v43
	v_rcp_f32_e32 v58, v43
	v_pk_fma_f32 v[32:33], v[54:55], v[60:61], v[32:33] op_sel:[1,0,0]
	v_add_f32_e32 v16, 1.0, v16
	v_rcp_f32_e32 v59, v16
	v_mul_f32_e32 v16, 0xbfb8aa3b, v50
	v_exp_f32_e32 v16, v16
	v_pk_mul_f32 v[56:57], v[58:59], v[56:57]
	s_nop 0
	v_pk_mul_f32 v[32:33], v[32:33], v[56:57]
	v_lshlrev_b32_e32 v56, 16, v17
	v_and_b32_e32 v57, 0xffff0000, v17
	v_mul_f32_e32 v17, 0xbfb8aa3b, v51
	v_exp_f32_e32 v17, v17
	v_add_f32_e32 v16, 1.0, v16
	v_rcp_f32_e32 v16, v16
	v_pk_fma_f32 v[34:35], v[54:55], v[56:57], v[34:35] op_sel:[1,0,0]
	v_add_f32_e32 v17, 1.0, v17
	v_rcp_f32_e32 v17, v17
	s_nop 0
	v_pk_mul_f32 v[16:17], v[16:17], v[50:51]
	s_nop 0
	v_pk_mul_f32 v[16:17], v[34:35], v[16:17]
	v_pk_mul_f32 v[34:35], v[32:33], v[32:33]
	v_pk_mul_f32 v[50:51], v[16:17], v[16:17]
	v_mov_b32_e32 v45, v34
	v_mov_b32_e32 v43, v35
	v_pk_add_f32 v[34:35], v[44:45], v[42:43]
	global_load_dwordx2 v[44:45], v[40:41], off offset:32
	v_mov_b32_e32 v47, v50
	v_mov_b32_e32 v49, v51
	v_pk_add_f32 v[42:43], v[46:47], v[48:49]
	v_lshlrev_b32_e32 v48, 16, v18
	v_pk_add_f32 v[34:35], v[34:35], v[42:43]
	v_and_b32_e32 v49, 0xffff0000, v18
	v_pk_add_f32 v[42:43], v[34:35], v[34:35] op_sel:[0,1] op_sel_hi:[1,0]
	v_pk_fma_f32 v[12:13], v[54:55], v[48:49], v[12:13] op_sel:[1,0,0]
	s_waitcnt vmcnt(0)
	v_lshlrev_b32_e32 v34, 16, v44
	v_and_b32_e32 v35, 0xffff0000, v44
	v_mul_f32_e32 v43, 0xbfb8aa3b, v34
	v_mul_f32_e32 v18, 0xbfb8aa3b, v35
	v_exp_f32_e32 v43, v43
	v_exp_f32_e32 v18, v18
	v_lshlrev_b32_e32 v44, 16, v19
	v_add_f32_e32 v43, 1.0, v43
	v_add_f32_e32 v18, 1.0, v18
	v_rcp_f32_e32 v46, v43
	v_rcp_f32_e32 v47, v18
	s_nop 0
	v_pk_mul_f32 v[34:35], v[46:47], v[34:35]
	global_load_dwordx2 v[46:47], v[40:41], off offset:64
	v_pk_mul_f32 v[34:35], v[12:13], v[34:35]
	global_load_dwordx2 v[40:41], v[40:41], off offset:96
	v_lshlrev_b32_e32 v12, 16, v45
	v_and_b32_e32 v13, 0xffff0000, v45
	v_mul_f32_e32 v18, 0xbfb8aa3b, v12
	v_and_b32_e32 v45, 0xffff0000, v19
	v_mul_f32_e32 v19, 0xbfb8aa3b, v13
	v_exp_f32_e32 v18, v18
	v_exp_f32_e32 v19, v19
	v_pk_fma_f32 v[14:15], v[54:55], v[44:45], v[14:15] op_sel:[1,0,0]
	v_add_f32_e32 v18, 1.0, v18
	v_add_f32_e32 v19, 1.0, v19
	v_rcp_f32_e32 v18, v18
	v_rcp_f32_e32 v19, v19
	s_waitcnt vmcnt(1)
	v_lshlrev_b32_e32 v48, 16, v46
	v_pk_mul_f32 v[12:13], v[18:19], v[12:13]
	v_and_b32_e32 v49, 0xffff0000, v46
	v_pk_mul_f32 v[18:19], v[14:15], v[12:13]
	v_mov_b32_e32 v14, v35
	v_mov_b32_e32 v15, v19
	v_mov_b32_e32 v12, v34
	v_mov_b32_e32 v13, v18
	v_pk_mul_f32 v[14:15], v[14:15], v[14:15]
	v_mul_f32_e32 v43, 0xbfb8aa3b, v48
	v_pk_fma_f32 v[12:13], v[12:13], v[12:13], v[14:15]
	v_exp_f32_e32 v43, v43
	v_pk_add_f32 v[44:45], v[12:13], v[12:13] op_sel:[0,1] op_sel_hi:[1,0]
	ds_read2_b64 v[12:15], v231 offset0:24 offset1:28
	v_lshlrev_b32_e32 v46, 16, v47
	v_add_f32_e32 v43, 1.0, v43
	v_rcp_f32_e32 v50, v43
	v_and_b32_e32 v47, 0xffff0000, v47
	s_waitcnt lgkmcnt(0)
	v_lshlrev_b32_e32 v56, 16, v12
	v_and_b32_e32 v57, 0xffff0000, v12
	v_mul_f32_e32 v12, 0xbfb8aa3b, v49
	v_exp_f32_e32 v12, v12
	v_pk_fma_f32 v[8:9], v[54:55], v[56:57], v[8:9] op_sel:[1,0,0]
	v_lshlrev_b32_e32 v56, 16, v14
	v_and_b32_e32 v57, 0xffff0000, v14
	v_add_f32_e32 v12, 1.0, v12
	v_rcp_f32_e32 v51, v12
	v_mul_f32_e32 v12, 0xbfb8aa3b, v46
	v_exp_f32_e32 v12, v12
	v_pk_fma_f32 v[4:5], v[54:55], v[56:57], v[4:5] op_sel:[1,0,0]
	v_pk_mul_f32 v[48:49], v[50:51], v[48:49]
	v_add_f32_e32 v12, 1.0, v12
	v_pk_mul_f32 v[8:9], v[8:9], v[48:49]
	v_lshlrev_b32_e32 v48, 16, v13
	v_and_b32_e32 v49, 0xffff0000, v13
	v_mul_f32_e32 v13, 0xbfb8aa3b, v47
	v_exp_f32_e32 v13, v13
	v_rcp_f32_e32 v12, v12
	v_pk_fma_f32 v[10:11], v[54:55], v[48:49], v[10:11] op_sel:[1,0,0]
	v_add_f32_e32 v13, 1.0, v13
	v_rcp_f32_e32 v13, v13
	s_nop 0
	v_pk_mul_f32 v[12:13], v[12:13], v[46:47]
	s_nop 0
	v_pk_mul_f32 v[10:11], v[10:11], v[12:13]
	v_mul_f32_e32 v12, v9, v9
	v_pk_fma_f32 v[46:47], v[8:9], v[8:9], v[12:13] op_sel_hi:[1,1,0]
	v_mul_f32_e32 v12, v11, v11
	v_pk_fma_f32 v[48:49], v[10:11], v[10:11], v[12:13] op_sel_hi:[1,1,0]
	s_waitcnt vmcnt(0)
; DI unsigned pk2(float lo, float hi) { f32x2_t v = {lo, hi}; bf16x2_t b = __builtin_convertvector(v, bf16x2_t); return __builtin_bit_cast(unsigned, b); }
; DI void ssd_part2_unit(int u, const bf16* PROJ, const float* DT, const float* cw, const float* cb, const float* a_log_l, const float* dskip_l, const float* snw_l,
;                        const float* STATES, bf16* YC, LAS unsigned char* ldsu, int tid, int wave, int lane) {
;     ...
;     ss += __shfl_xor(ss, 16); ss += __shfl_xor(ss, 32);
;     const float rstd = rsqrtf(ss * (1.f / 128.f) + EPS);
; #pragma unroll
;     for (int hh = 0; hh < 2; ++hh)
; #pragma unroll
;         for (int pt = 0; pt < 4; ++pt) { const int ch = grp * 128 + hh * 64 + 16 * pt + 4 * g;
;             const f32x4 nw = *(const f32x4*)(snw_l + ch); const f32x4 y = acc[hh][pt] * rstd * nw;
;             u32x2 w; w.x = pk2(y[0], y[1]); w.y = pk2(y[2], y[3]);
;             *(u32x2*)(YC + (size_t)(b * T + token) * 1024 + 512 + ch) = w; }
	v_lshlrev_b32_e32 v12, 16, v40
	v_and_b32_e32 v13, 0xffff0000, v40
	v_mul_f32_e32 v40, 0xbfb8aa3b, v12
	v_mul_f32_e32 v14, 0xbfb8aa3b, v13
	v_exp_f32_e32 v40, v40
	v_exp_f32_e32 v14, v14
	v_add_f32_e32 v40, 1.0, v40
	v_add_f32_e32 v14, 1.0, v14
	v_rcp_f32_e32 v50, v40
	v_rcp_f32_e32 v51, v14
	v_lshlrev_b32_e32 v40, 16, v15
	v_pk_mul_f32 v[12:13], v[50:51], v[12:13]
	s_nop 0
	v_pk_mul_f32 v[12:13], v[4:5], v[12:13]
	v_lshlrev_b32_e32 v4, 16, v41
	v_and_b32_e32 v5, 0xffff0000, v41
	v_mul_f32_e32 v14, 0xbfb8aa3b, v4
	v_and_b32_e32 v41, 0xffff0000, v15
	v_mul_f32_e32 v15, 0xbfb8aa3b, v5
	v_exp_f32_e32 v14, v14
	v_exp_f32_e32 v15, v15
	v_pk_fma_f32 v[6:7], v[54:55], v[40:41], v[6:7] op_sel:[1,0,0]
	v_or_b32_e32 v41, s34, v204
	v_add_f32_e32 v14, 1.0, v14
	v_add_f32_e32 v15, 1.0, v15
	v_rcp_f32_e32 v14, v14
	v_rcp_f32_e32 v15, v15
	v_lshlrev_b32_e32 v188, 1, v41
	v_pk_mul_f32 v[4:5], v[14:15], v[4:5]
	s_nop 0
	v_pk_mul_f32 v[14:15], v[6:7], v[4:5]
	v_pk_mul_f32 v[4:5], v[12:13], v[12:13]
	v_pk_mul_f32 v[6:7], v[14:15], v[14:15]
	v_mov_b32_e32 v43, v4
	v_mov_b32_e32 v45, v5
	v_mov_b32_e32 v47, v6
	v_mov_b32_e32 v49, v7
	v_pk_add_f32 v[4:5], v[42:43], v[44:45]
	v_pk_add_f32 v[6:7], v[46:47], v[48:49]
	v_lshlrev_b32_e32 v44, 2, v41
	v_pk_add_f32 v[4:5], v[4:5], v[6:7]
	s_nop 0
	v_add_f32_e32 v4, v4, v5
	ds_bpermute_b32 v5, v223, v4
	s_waitcnt lgkmcnt(0)
	v_add_f32_e32 v4, v4, v5
	ds_bpermute_b32 v5, v242, v4
	s_waitcnt lgkmcnt(0)
	v_add_f32_e32 v4, v4, v5
	v_fmamk_f32 v4, v4, 0x3c000000, v190
	v_cmp_gt_f32_e32 vcc, s15, v4
	v_mul_f32_e32 v5, 0x4b800000, v4
	s_nop 0
	v_cndmask_b32_e32 v4, v4, v5, vcc
	v_rsq_f32_e32 v4, v4
	s_nop 0
	v_mul_f32_e32 v5, 0x45800000, v4
	v_cndmask_b32_e32 v40, v4, v5, vcc
	v_lshl_add_u32 v4, s94, 11, v52
	v_ashrrev_i32_e32 v5, 31, v4
	v_lshlrev_b64 v[4:5], 11, v[4:5]
	v_lshl_add_u64 v[42:43], s[8:9], 0, v[4:5]
	global_load_dwordx4 v[60:63], v44, s[90:91]
	global_load_dwordx4 v[64:67], v44, s[90:91] offset:64
	global_load_dwordx4 v[68:71], v44, s[90:91] offset:128
	global_load_dwordx4 v[72:75], v44, s[90:91] offset:192
	global_load_dwordx4 v[76:79], v44, s[90:91] offset:256
	global_load_dwordx4 v[80:83], v44, s[90:91] offset:320
	global_load_dwordx4 v[84:87], v44, s[90:91] offset:384
	global_load_dwordx4 v[88:91], v44, s[90:91] offset:448
	v_pk_mul_f32 v[20:21], v[20:21], v[40:41] op_sel_hi:[1,0]
	v_pk_mul_f32 v[22:23], v[22:23], v[40:41] op_sel_hi:[1,0]
	v_pk_mul_f32 v[16:17], v[16:17], v[40:41] op_sel_hi:[1,0]
	v_pk_mul_f32 v[18:19], v[18:19], v[40:41] op_sel_hi:[1,0]
	v_pk_mul_f32 v[8:9], v[8:9], v[40:41] op_sel_hi:[1,0]
	v_pk_mul_f32 v[10:11], v[10:11], v[40:41] op_sel_hi:[1,0]
	s_waitcnt vmcnt(0)
	v_pk_mul_f32 v[6:7], v[62:63], v[22:23]
	v_pk_mul_f32 v[4:5], v[60:61], v[20:21]
	v_lshl_add_u64 v[20:21], v[42:43], 0, v[188:189]
	v_cvt_pk_bf16_f32 v4, v4, v5
	v_cvt_pk_bf16_f32 v5, v6, v7
	global_store_dwordx2 v[20:21], v[4:5], off offset:1024
	v_pk_mul_f32 v[22:23], v[24:25], v[40:41] op_sel_hi:[1,0]
	v_pk_mul_f32 v[24:25], v[26:27], v[40:41] op_sel_hi:[1,0]
	v_pk_mul_f32 v[4:5], v[64:65], v[22:23]
	v_pk_mul_f32 v[6:7], v[66:67], v[24:25]
	v_cvt_pk_bf16_f32 v4, v4, v5
	v_cvt_pk_bf16_f32 v5, v6, v7
	global_store_dwordx2 v[20:21], v[4:5], off offset:1056
	v_pk_mul_f32 v[22:23], v[28:29], v[40:41] op_sel_hi:[1,0]
	v_pk_mul_f32 v[24:25], v[30:31], v[40:41] op_sel_hi:[1,0]
	v_pk_mul_f32 v[4:5], v[68:69], v[22:23]
	v_pk_mul_f32 v[6:7], v[70:71], v[24:25]
	v_cvt_pk_bf16_f32 v4, v4, v5
	v_cvt_pk_bf16_f32 v5, v6, v7
	global_store_dwordx2 v[20:21], v[4:5], off offset:1088
	v_pk_mul_f32 v[22:23], v[36:37], v[40:41] op_sel_hi:[1,0]
	v_pk_mul_f32 v[24:25], v[38:39], v[40:41] op_sel_hi:[1,0]
	v_pk_mul_f32 v[4:5], v[72:73], v[22:23]
	v_pk_mul_f32 v[6:7], v[74:75], v[24:25]
	v_cvt_pk_bf16_f32 v4, v4, v5
	v_cvt_pk_bf16_f32 v5, v6, v7
	global_store_dwordx2 v[20:21], v[4:5], off offset:1120
	v_pk_mul_f32 v[22:23], v[32:33], v[40:41] op_sel_hi:[1,0]
	v_pk_mul_f32 v[6:7], v[78:79], v[16:17]
	v_pk_mul_f32 v[4:5], v[76:77], v[22:23]
	v_pk_mul_f32 v[16:17], v[34:35], v[40:41] op_sel_hi:[1,0]
	v_cvt_pk_bf16_f32 v4, v4, v5
	v_cvt_pk_bf16_f32 v5, v6, v7
	global_store_dwordx2 v[20:21], v[4:5], off offset:1152
	v_pk_mul_f32 v[6:7], v[82:83], v[18:19]
	v_pk_mul_f32 v[4:5], v[80:81], v[16:17]
	s_nop 0
	v_cvt_pk_bf16_f32 v4, v4, v5
	v_cvt_pk_bf16_f32 v5, v6, v7
	global_store_dwordx2 v[20:21], v[4:5], off offset:1184
	v_pk_mul_f32 v[6:7], v[86:87], v[10:11]
	v_pk_mul_f32 v[4:5], v[84:85], v[8:9]
	v_pk_mul_f32 v[8:9], v[12:13], v[40:41] op_sel_hi:[1,0]
	v_cvt_pk_bf16_f32 v4, v4, v5
	v_cvt_pk_bf16_f32 v5, v6, v7
	global_store_dwordx2 v[20:21], v[4:5], off offset:1216
	v_pk_mul_f32 v[10:11], v[14:15], v[40:41] op_sel_hi:[1,0]
	v_pk_mul_f32 v[4:5], v[88:89], v[8:9]
	v_pk_mul_f32 v[6:7], v[90:91], v[10:11]
	v_cvt_pk_bf16_f32 v4, v4, v5
	v_cvt_pk_bf16_f32 v5, v6, v7
	global_store_dwordx2 v[20:21], v[4:5], off offset:1248
	s_cbranch_scc1 .LBB0_523
